# layer-1 input projection epilogue rewritten by hand: scalar tile bases + one lane offset, global stores, packed SiLU math; on top of static-priority version
# baseline (speedup 1.0000x reference)
; __device__ __forceinline__ unsigned pk_bf16(float lo, float hi) { const f32x2 v = {lo, hi}; return __builtin_bit_cast(unsigned, __builtin_convertvector(v, nbf16x2)); }
;     __device__ __forceinline__ void store8(int row, int col, const f32x4 v, const f32x4 w) const { st8_bf16((bf16_t*)((unsigned char*)out + T_D0) + (size_t)row * DM + col, v, w); }
;     __device__ __forceinline__ void store8(int row, int col, const f32x4 v, const f32x4 w) const { store4(row, col, v); store4(row, col + 4, w); }
; __device__ __forceinline__ void st8_bf16(bf16_t* p, const f32x4 a, const f32x4 b) { __builtin_nontemporal_store((u32x4){pk_bf16(a[0], a[1]), pk_bf16(a[2], a[3]), pk_bf16(b[0], b[1]), pk_bf16(b[2], b[3])}, (u32x4*)p); }
; __device__ __forceinline__ void st8_f32(float* p, const f32x4 a, const f32x4 b) { __builtin_nontemporal_store(a, (f32x4*)p); __builtin_nontemporal_store(b, (f32x4*)(p + 4)); }
; __device__ __forceinline__ f32x4 silu4(const f32x4 v) { return (f32x4){v[0] / (1.f + __expf(-v[0])), v[1] / (1.f + __expf(-v[1])), v[2] / (1.f + __expf(-v[2])), v[3] / (1.f + __expf(-v[3]))}; }
;     __device__ __forceinline__ void store8(int row, int col, const f32x4 v, const f32x4 w) const {
;         if (col < 1536) st8_bf16((bf16_t*)(ws + WS_BRANCH) + (size_t)row * BR + col, v, w);
;         else if (col < 3072) { const int c = col - 1536; st8_bf16((bf16_t*)(ws + WS_KB) + (size_t)row * MIXW + c, v, w);
;             if (row < MP) st8_f32(out + O_PK + (size_t)row * MIXW + c, v, w); else st8_f32(out + O_SK + (size_t)(row - MP) * MIXW + c, v, w); }
;         else if (col < 4608) { const int c = col - 3072; st8_bf16((bf16_t*)(ws + WS_VB) + (size_t)row * MIXW + c, v, w);
;             if (row < MP) st8_f32(out + O_PV + (size_t)row * MIXW + c, v, w); else st8_f32(out + O_SV + (size_t)(row - MP) * MIXW + c, v, w); }
;         else if (col < 5120) st8_bf16((bf16_t*)(ws + WS_BRANCH) + (size_t)row * BR + 1536 + (col - 4608), v, w);
;         else st8_bf16((bf16_t*)(ws + WS_GATE) + (size_t)row * BR + (col - 5120), silu4(v), silu4(w));
;     }
.LBB0_733:
	s_lshl_b32 s84, s8, 8
	s_cmp_lt_u32 s6, 6
	s_cbranch_scc1 .Le6_q
	s_cmp_lt_u32 s6, 12
	s_cbranch_scc1 .Le6_k
	s_cmp_lt_u32 s6, 18
	s_cbranch_scc1 .Le6_v
	s_cmp_lt_u32 s6, 20
	s_cbranch_scc1 .Le6_b2
.Le6_g:
	s_mul_i32 s85, s84, 0x1000
	s_add_u32 s86, s14, s85
	s_addc_u32 s87, s15, 0
	s_add_u32 s86, s86, 0x15ae0000
	s_addc_u32 s87, s87, 0
	s_sub_i32 s85, s6, 20
	s_lshl_b32 s85, s85, 9
	s_add_u32 s86, s86, s85
	s_addc_u32 s87, s87, 0
	v_lshlrev_b32_e32 v146, 1, v154
	s_movk_i32 s85, 0x1000
	v_mad_u32_u24 v146, v152, s85, v146
	s_mov_b32 s98, 0xbfb8aa3b
	s_mov_b32 s99, 0xbfb8aa3b
	s_mov_b64 s[92:93], s[86:87]
	v_pk_mul_f32 v[148:149], v[124:125], s[98:99]
	v_pk_mul_f32 v[150:151], v[126:127], s[98:99]
	v_pk_mul_f32 v[164:165], v[120:121], s[98:99]
	v_pk_mul_f32 v[166:167], v[122:123], s[98:99]
	v_exp_f32_e32 v148, v148
	v_exp_f32_e32 v149, v149
	v_exp_f32_e32 v150, v150
	v_exp_f32_e32 v151, v151
	v_exp_f32_e32 v164, v164
	v_exp_f32_e32 v165, v165
	v_exp_f32_e32 v166, v166
	v_exp_f32_e32 v167, v167
	v_pk_add_f32 v[148:149], v[148:149], 1.0 op_sel_hi:[1,0]
	v_pk_add_f32 v[150:151], v[150:151], 1.0 op_sel_hi:[1,0]
	v_pk_add_f32 v[164:165], v[164:165], 1.0 op_sel_hi:[1,0]
	v_pk_add_f32 v[166:167], v[166:167], 1.0 op_sel_hi:[1,0]
	v_rcp_f32_e32 v148, v148
	v_rcp_f32_e32 v149, v149
	v_rcp_f32_e32 v150, v150
	v_rcp_f32_e32 v151, v151
	v_rcp_f32_e32 v164, v164
	v_rcp_f32_e32 v165, v165
	v_rcp_f32_e32 v166, v166
	v_rcp_f32_e32 v167, v167
	v_pk_mul_f32 v[124:125], v[124:125], v[148:149]
	v_pk_mul_f32 v[126:127], v[126:127], v[150:151]
	v_pk_mul_f32 v[120:121], v[120:121], v[164:165]
	v_pk_mul_f32 v[122:123], v[122:123], v[166:167]
	v_cvt_pk_bf16_f32 v124, v124, v125
	v_cvt_pk_bf16_f32 v125, v126, v127
	v_cvt_pk_bf16_f32 v126, v120, v121
	v_cvt_pk_bf16_f32 v127, v122, v123
	global_store_dwordx4 v146, v[124:127], s[92:93] nt
	s_add_u32 s92, s86, 0x10000
	s_addc_u32 s93, s87, 0
	v_pk_mul_f32 v[148:149], v[116:117], s[98:99]
	v_pk_mul_f32 v[150:151], v[118:119], s[98:99]
	v_pk_mul_f32 v[164:165], v[112:113], s[98:99]
	v_pk_mul_f32 v[166:167], v[114:115], s[98:99]
	v_exp_f32_e32 v148, v148
	v_exp_f32_e32 v149, v149
	v_exp_f32_e32 v150, v150
	v_exp_f32_e32 v151, v151
	v_exp_f32_e32 v164, v164
	v_exp_f32_e32 v165, v165
	v_exp_f32_e32 v166, v166
	v_exp_f32_e32 v167, v167
	v_pk_add_f32 v[148:149], v[148:149], 1.0 op_sel_hi:[1,0]
	v_pk_add_f32 v[150:151], v[150:151], 1.0 op_sel_hi:[1,0]
	v_pk_add_f32 v[164:165], v[164:165], 1.0 op_sel_hi:[1,0]
	v_pk_add_f32 v[166:167], v[166:167], 1.0 op_sel_hi:[1,0]
	v_rcp_f32_e32 v148, v148
	v_rcp_f32_e32 v149, v149
	v_rcp_f32_e32 v150, v150
	v_rcp_f32_e32 v151, v151
	v_rcp_f32_e32 v164, v164
	v_rcp_f32_e32 v165, v165
	v_rcp_f32_e32 v166, v166
	v_rcp_f32_e32 v167, v167
	v_pk_mul_f32 v[116:117], v[116:117], v[148:149]
	v_pk_mul_f32 v[118:119], v[118:119], v[150:151]
	v_pk_mul_f32 v[112:113], v[112:113], v[164:165]
	v_pk_mul_f32 v[114:115], v[114:115], v[166:167]
	v_cvt_pk_bf16_f32 v116, v116, v117
	v_cvt_pk_bf16_f32 v117, v118, v119
	v_cvt_pk_bf16_f32 v118, v112, v113
	v_cvt_pk_bf16_f32 v119, v114, v115
	global_store_dwordx4 v146, v[116:119], s[92:93] nt
	s_add_u32 s92, s86, 0x20000
	s_addc_u32 s93, s87, 0
	v_pk_mul_f32 v[148:149], v[108:109], s[98:99]
	v_pk_mul_f32 v[150:151], v[110:111], s[98:99]
	v_pk_mul_f32 v[164:165], v[104:105], s[98:99]
	v_pk_mul_f32 v[166:167], v[106:107], s[98:99]
	v_exp_f32_e32 v148, v148
	v_exp_f32_e32 v149, v149
	v_exp_f32_e32 v150, v150
	v_exp_f32_e32 v151, v151
	v_exp_f32_e32 v164, v164
	v_exp_f32_e32 v165, v165
	v_exp_f32_e32 v166, v166
	v_exp_f32_e32 v167, v167
	v_pk_add_f32 v[148:149], v[148:149], 1.0 op_sel_hi:[1,0]
	v_pk_add_f32 v[150:151], v[150:151], 1.0 op_sel_hi:[1,0]
	v_pk_add_f32 v[164:165], v[164:165], 1.0 op_sel_hi:[1,0]
	v_pk_add_f32 v[166:167], v[166:167], 1.0 op_sel_hi:[1,0]
	v_rcp_f32_e32 v148, v148
	v_rcp_f32_e32 v149, v149
	v_rcp_f32_e32 v150, v150
	v_rcp_f32_e32 v151, v151
	v_rcp_f32_e32 v164, v164
	v_rcp_f32_e32 v165, v165
	v_rcp_f32_e32 v166, v166
	v_rcp_f32_e32 v167, v167
	v_pk_mul_f32 v[108:109], v[108:109], v[148:149]
	v_pk_mul_f32 v[110:111], v[110:111], v[150:151]
	v_pk_mul_f32 v[104:105], v[104:105], v[164:165]
	v_pk_mul_f32 v[106:107], v[106:107], v[166:167]
	v_cvt_pk_bf16_f32 v108, v108, v109
	v_cvt_pk_bf16_f32 v109, v110, v111
	v_cvt_pk_bf16_f32 v110, v104, v105
	v_cvt_pk_bf16_f32 v111, v106, v107
	global_store_dwordx4 v146, v[108:111], s[92:93] nt
	s_add_u32 s92, s86, 0x30000
	s_addc_u32 s93, s87, 0
	v_pk_mul_f32 v[148:149], v[100:101], s[98:99]
	v_pk_mul_f32 v[150:151], v[102:103], s[98:99]
	v_pk_mul_f32 v[164:165], v[96:97], s[98:99]
	v_pk_mul_f32 v[166:167], v[98:99], s[98:99]
	v_exp_f32_e32 v148, v148
	v_exp_f32_e32 v149, v149
	v_exp_f32_e32 v150, v150
	v_exp_f32_e32 v151, v151
	v_exp_f32_e32 v164, v164
	v_exp_f32_e32 v165, v165
	v_exp_f32_e32 v166, v166
	v_exp_f32_e32 v167, v167
	v_pk_add_f32 v[148:149], v[148:149], 1.0 op_sel_hi:[1,0]
	v_pk_add_f32 v[150:151], v[150:151], 1.0 op_sel_hi:[1,0]
	v_pk_add_f32 v[164:165], v[164:165], 1.0 op_sel_hi:[1,0]
	v_pk_add_f32 v[166:167], v[166:167], 1.0 op_sel_hi:[1,0]
	v_rcp_f32_e32 v148, v148
	v_rcp_f32_e32 v149, v149
	v_rcp_f32_e32 v150, v150
	v_rcp_f32_e32 v151, v151
	v_rcp_f32_e32 v164, v164
	v_rcp_f32_e32 v165, v165
	v_rcp_f32_e32 v166, v166
	v_rcp_f32_e32 v167, v167
	v_pk_mul_f32 v[100:101], v[100:101], v[148:149]
	v_pk_mul_f32 v[102:103], v[102:103], v[150:151]
	v_pk_mul_f32 v[96:97], v[96:97], v[164:165]
	v_pk_mul_f32 v[98:99], v[98:99], v[166:167]
	v_cvt_pk_bf16_f32 v100, v100, v101
	v_cvt_pk_bf16_f32 v101, v102, v103
	v_cvt_pk_bf16_f32 v102, v96, v97
	v_cvt_pk_bf16_f32 v103, v98, v99
; __device__ __forceinline__ unsigned pk_bf16(float lo, float hi) { const f32x2 v = {lo, hi}; return __builtin_bit_cast(unsigned, __builtin_convertvector(v, nbf16x2)); }
; __device__ __forceinline__ void st8_bf16(bf16_t* p, const f32x4 a, const f32x4 b) { __builtin_nontemporal_store((u32x4){pk_bf16(a[0], a[1]), pk_bf16(a[2], a[3]), pk_bf16(b[0], b[1]), pk_bf16(b[2], b[3])}, (u32x4*)p); }
; __device__ __forceinline__ void st8_f32(float* p, const f32x4 a, const f32x4 b) { __builtin_nontemporal_store(a, (f32x4*)p); __builtin_nontemporal_store(b, (f32x4*)(p + 4)); }
; __device__ __forceinline__ f32x4 silu4(const f32x4 v) { return (f32x4){v[0] / (1.f + __expf(-v[0])), v[1] / (1.f + __expf(-v[1])), v[2] / (1.f + __expf(-v[2])), v[3] / (1.f + __expf(-v[3]))}; }
;     __device__ __forceinline__ void store8(int row, int col, const f32x4 v, const f32x4 w) const {
;     ...
;         else st8_bf16((bf16_t*)(ws + WS_GATE) + (size_t)row * BR + (col - 5120), silu4(v), silu4(w));
	global_store_dwordx4 v146, v[100:103], s[92:93] nt
	s_add_u32 s92, s86, 0x100
	s_addc_u32 s93, s87, 0
	v_pk_mul_f32 v[148:149], v[92:93], s[98:99]
	v_pk_mul_f32 v[150:151], v[94:95], s[98:99]
	v_pk_mul_f32 v[164:165], v[88:89], s[98:99]
	v_pk_mul_f32 v[166:167], v[90:91], s[98:99]
	v_exp_f32_e32 v148, v148
	v_exp_f32_e32 v149, v149
	v_exp_f32_e32 v150, v150
	v_exp_f32_e32 v151, v151
	v_exp_f32_e32 v164, v164
	v_exp_f32_e32 v165, v165
	v_exp_f32_e32 v166, v166
	v_exp_f32_e32 v167, v167
	v_pk_add_f32 v[148:149], v[148:149], 1.0 op_sel_hi:[1,0]
	v_pk_add_f32 v[150:151], v[150:151], 1.0 op_sel_hi:[1,0]
	v_pk_add_f32 v[164:165], v[164:165], 1.0 op_sel_hi:[1,0]
	v_pk_add_f32 v[166:167], v[166:167], 1.0 op_sel_hi:[1,0]
	v_rcp_f32_e32 v148, v148
	v_rcp_f32_e32 v149, v149
	v_rcp_f32_e32 v150, v150
	v_rcp_f32_e32 v151, v151
	v_rcp_f32_e32 v164, v164
	v_rcp_f32_e32 v165, v165
	v_rcp_f32_e32 v166, v166
	v_rcp_f32_e32 v167, v167
	v_pk_mul_f32 v[92:93], v[92:93], v[148:149]
	v_pk_mul_f32 v[94:95], v[94:95], v[150:151]
	v_pk_mul_f32 v[88:89], v[88:89], v[164:165]
	v_pk_mul_f32 v[90:91], v[90:91], v[166:167]
	v_cvt_pk_bf16_f32 v92, v92, v93
	v_cvt_pk_bf16_f32 v93, v94, v95
	v_cvt_pk_bf16_f32 v94, v88, v89
	v_cvt_pk_bf16_f32 v95, v90, v91
	global_store_dwordx4 v146, v[92:95], s[92:93] nt
	s_add_u32 s92, s86, 0x10100
	s_addc_u32 s93, s87, 0
	v_pk_mul_f32 v[148:149], v[84:85], s[98:99]
	v_pk_mul_f32 v[150:151], v[86:87], s[98:99]
	v_pk_mul_f32 v[164:165], v[80:81], s[98:99]
	v_pk_mul_f32 v[166:167], v[82:83], s[98:99]
	v_exp_f32_e32 v148, v148
	v_exp_f32_e32 v149, v149
	v_exp_f32_e32 v150, v150
	v_exp_f32_e32 v151, v151
	v_exp_f32_e32 v164, v164
	v_exp_f32_e32 v165, v165
	v_exp_f32_e32 v166, v166
	v_exp_f32_e32 v167, v167
	v_pk_add_f32 v[148:149], v[148:149], 1.0 op_sel_hi:[1,0]
	v_pk_add_f32 v[150:151], v[150:151], 1.0 op_sel_hi:[1,0]
	v_pk_add_f32 v[164:165], v[164:165], 1.0 op_sel_hi:[1,0]
	v_pk_add_f32 v[166:167], v[166:167], 1.0 op_sel_hi:[1,0]
	v_rcp_f32_e32 v148, v148
	v_rcp_f32_e32 v149, v149
	v_rcp_f32_e32 v150, v150
	v_rcp_f32_e32 v151, v151
	v_rcp_f32_e32 v164, v164
	v_rcp_f32_e32 v165, v165
	v_rcp_f32_e32 v166, v166
	v_rcp_f32_e32 v167, v167
	v_pk_mul_f32 v[84:85], v[84:85], v[148:149]
	v_pk_mul_f32 v[86:87], v[86:87], v[150:151]
	v_pk_mul_f32 v[80:81], v[80:81], v[164:165]
	v_pk_mul_f32 v[82:83], v[82:83], v[166:167]
	v_cvt_pk_bf16_f32 v84, v84, v85
	v_cvt_pk_bf16_f32 v85, v86, v87
	v_cvt_pk_bf16_f32 v86, v80, v81
	v_cvt_pk_bf16_f32 v87, v82, v83
	global_store_dwordx4 v146, v[84:87], s[92:93] nt
	s_add_u32 s92, s86, 0x20100
	s_addc_u32 s93, s87, 0
	v_pk_mul_f32 v[148:149], v[76:77], s[98:99]
	v_pk_mul_f32 v[150:151], v[78:79], s[98:99]
	v_pk_mul_f32 v[164:165], v[72:73], s[98:99]
	v_pk_mul_f32 v[166:167], v[74:75], s[98:99]
	v_exp_f32_e32 v148, v148
	v_exp_f32_e32 v149, v149
	v_exp_f32_e32 v150, v150
	v_exp_f32_e32 v151, v151
	v_exp_f32_e32 v164, v164
	v_exp_f32_e32 v165, v165
	v_exp_f32_e32 v166, v166
	v_exp_f32_e32 v167, v167
	v_pk_add_f32 v[148:149], v[148:149], 1.0 op_sel_hi:[1,0]
	v_pk_add_f32 v[150:151], v[150:151], 1.0 op_sel_hi:[1,0]
	v_pk_add_f32 v[164:165], v[164:165], 1.0 op_sel_hi:[1,0]
	v_pk_add_f32 v[166:167], v[166:167], 1.0 op_sel_hi:[1,0]
	v_rcp_f32_e32 v148, v148
	v_rcp_f32_e32 v149, v149
	v_rcp_f32_e32 v150, v150
	v_rcp_f32_e32 v151, v151
	v_rcp_f32_e32 v164, v164
	v_rcp_f32_e32 v165, v165
	v_rcp_f32_e32 v166, v166
	v_rcp_f32_e32 v167, v167
	v_pk_mul_f32 v[76:77], v[76:77], v[148:149]
	v_pk_mul_f32 v[78:79], v[78:79], v[150:151]
	v_pk_mul_f32 v[72:73], v[72:73], v[164:165]
	v_pk_mul_f32 v[74:75], v[74:75], v[166:167]
	v_cvt_pk_bf16_f32 v76, v76, v77
	v_cvt_pk_bf16_f32 v77, v78, v79
	v_cvt_pk_bf16_f32 v78, v72, v73
	v_cvt_pk_bf16_f32 v79, v74, v75
	global_store_dwordx4 v146, v[76:79], s[92:93] nt
	s_add_u32 s92, s86, 0x30100
	s_addc_u32 s93, s87, 0
	v_pk_mul_f32 v[148:149], v[68:69], s[98:99]
	v_pk_mul_f32 v[150:151], v[70:71], s[98:99]
	v_pk_mul_f32 v[164:165], v[64:65], s[98:99]
	v_pk_mul_f32 v[166:167], v[66:67], s[98:99]
	v_exp_f32_e32 v148, v148
	v_exp_f32_e32 v149, v149
	v_exp_f32_e32 v150, v150
	v_exp_f32_e32 v151, v151
	v_exp_f32_e32 v164, v164
	v_exp_f32_e32 v165, v165
	v_exp_f32_e32 v166, v166
	v_exp_f32_e32 v167, v167
	v_pk_add_f32 v[148:149], v[148:149], 1.0 op_sel_hi:[1,0]
	v_pk_add_f32 v[150:151], v[150:151], 1.0 op_sel_hi:[1,0]
	v_pk_add_f32 v[164:165], v[164:165], 1.0 op_sel_hi:[1,0]
	v_pk_add_f32 v[166:167], v[166:167], 1.0 op_sel_hi:[1,0]
	v_rcp_f32_e32 v148, v148
	v_rcp_f32_e32 v149, v149
	v_rcp_f32_e32 v150, v150
	v_rcp_f32_e32 v151, v151
	v_rcp_f32_e32 v164, v164
	v_rcp_f32_e32 v165, v165
	v_rcp_f32_e32 v166, v166
	v_rcp_f32_e32 v167, v167
	v_pk_mul_f32 v[68:69], v[68:69], v[148:149]
	v_pk_mul_f32 v[70:71], v[70:71], v[150:151]
	v_pk_mul_f32 v[64:65], v[64:65], v[164:165]
	v_pk_mul_f32 v[66:67], v[66:67], v[166:167]
	v_cvt_pk_bf16_f32 v68, v68, v69
	v_cvt_pk_bf16_f32 v69, v70, v71
	v_cvt_pk_bf16_f32 v70, v64, v65
	v_cvt_pk_bf16_f32 v71, v66, v67
	global_store_dwordx4 v146, v[68:71], s[92:93] nt
	s_add_u32 s92, s86, 0x80000
	s_addc_u32 s93, s87, 0
	v_pk_mul_f32 v[148:149], v[60:61], s[98:99]
	v_pk_mul_f32 v[150:151], v[62:63], s[98:99]
	v_pk_mul_f32 v[164:165], v[56:57], s[98:99]
	v_pk_mul_f32 v[166:167], v[58:59], s[98:99]
	v_exp_f32_e32 v148, v148
	v_exp_f32_e32 v149, v149
	v_exp_f32_e32 v150, v150
	v_exp_f32_e32 v151, v151
	v_exp_f32_e32 v164, v164
	v_exp_f32_e32 v165, v165
	v_exp_f32_e32 v166, v166
	v_exp_f32_e32 v167, v167
	v_pk_add_f32 v[148:149], v[148:149], 1.0 op_sel_hi:[1,0]
	v_pk_add_f32 v[150:151], v[150:151], 1.0 op_sel_hi:[1,0]
	v_pk_add_f32 v[164:165], v[164:165], 1.0 op_sel_hi:[1,0]
; __device__ __forceinline__ unsigned pk_bf16(float lo, float hi) { const f32x2 v = {lo, hi}; return __builtin_bit_cast(unsigned, __builtin_convertvector(v, nbf16x2)); }
; __device__ __forceinline__ void st8_bf16(bf16_t* p, const f32x4 a, const f32x4 b) { __builtin_nontemporal_store((u32x4){pk_bf16(a[0], a[1]), pk_bf16(a[2], a[3]), pk_bf16(b[0], b[1]), pk_bf16(b[2], b[3])}, (u32x4*)p); }
; __device__ __forceinline__ void st8_f32(float* p, const f32x4 a, const f32x4 b) { __builtin_nontemporal_store(a, (f32x4*)p); __builtin_nontemporal_store(b, (f32x4*)(p + 4)); }
; __device__ __forceinline__ f32x4 silu4(const f32x4 v) { return (f32x4){v[0] / (1.f + __expf(-v[0])), v[1] / (1.f + __expf(-v[1])), v[2] / (1.f + __expf(-v[2])), v[3] / (1.f + __expf(-v[3]))}; }
;     __device__ __forceinline__ void store8(int row, int col, const f32x4 v, const f32x4 w) const {
;     ...
;         else st8_bf16((bf16_t*)(ws + WS_GATE) + (size_t)row * BR + (col - 5120), silu4(v), silu4(w));
	v_pk_add_f32 v[166:167], v[166:167], 1.0 op_sel_hi:[1,0]
	v_rcp_f32_e32 v148, v148
	v_rcp_f32_e32 v149, v149
	v_rcp_f32_e32 v150, v150
	v_rcp_f32_e32 v151, v151
	v_rcp_f32_e32 v164, v164
	v_rcp_f32_e32 v165, v165
	v_rcp_f32_e32 v166, v166
	v_rcp_f32_e32 v167, v167
	v_pk_mul_f32 v[60:61], v[60:61], v[148:149]
	v_pk_mul_f32 v[62:63], v[62:63], v[150:151]
	v_pk_mul_f32 v[56:57], v[56:57], v[164:165]
	v_pk_mul_f32 v[58:59], v[58:59], v[166:167]
	v_cvt_pk_bf16_f32 v60, v60, v61
	v_cvt_pk_bf16_f32 v61, v62, v63
	v_cvt_pk_bf16_f32 v62, v56, v57
	v_cvt_pk_bf16_f32 v63, v58, v59
	global_store_dwordx4 v146, v[60:63], s[92:93] nt
	s_add_u32 s92, s86, 0x90000
	s_addc_u32 s93, s87, 0
	v_pk_mul_f32 v[148:149], v[52:53], s[98:99]
	v_pk_mul_f32 v[150:151], v[54:55], s[98:99]
	v_pk_mul_f32 v[164:165], v[48:49], s[98:99]
	v_pk_mul_f32 v[166:167], v[50:51], s[98:99]
	v_exp_f32_e32 v148, v148
	v_exp_f32_e32 v149, v149
	v_exp_f32_e32 v150, v150
	v_exp_f32_e32 v151, v151
	v_exp_f32_e32 v164, v164
	v_exp_f32_e32 v165, v165
	v_exp_f32_e32 v166, v166
	v_exp_f32_e32 v167, v167
	v_pk_add_f32 v[148:149], v[148:149], 1.0 op_sel_hi:[1,0]
	v_pk_add_f32 v[150:151], v[150:151], 1.0 op_sel_hi:[1,0]
	v_pk_add_f32 v[164:165], v[164:165], 1.0 op_sel_hi:[1,0]
	v_pk_add_f32 v[166:167], v[166:167], 1.0 op_sel_hi:[1,0]
	v_rcp_f32_e32 v148, v148
	v_rcp_f32_e32 v149, v149
	v_rcp_f32_e32 v150, v150
	v_rcp_f32_e32 v151, v151
	v_rcp_f32_e32 v164, v164
	v_rcp_f32_e32 v165, v165
	v_rcp_f32_e32 v166, v166
	v_rcp_f32_e32 v167, v167
	v_pk_mul_f32 v[52:53], v[52:53], v[148:149]
	v_pk_mul_f32 v[54:55], v[54:55], v[150:151]
	v_pk_mul_f32 v[48:49], v[48:49], v[164:165]
	v_pk_mul_f32 v[50:51], v[50:51], v[166:167]
	v_cvt_pk_bf16_f32 v52, v52, v53
	v_cvt_pk_bf16_f32 v53, v54, v55
	v_cvt_pk_bf16_f32 v54, v48, v49
	v_cvt_pk_bf16_f32 v55, v50, v51
	global_store_dwordx4 v146, v[52:55], s[92:93] nt
	s_add_u32 s92, s86, 0xa0000
	s_addc_u32 s93, s87, 0
	v_pk_mul_f32 v[148:149], v[44:45], s[98:99]
	v_pk_mul_f32 v[150:151], v[46:47], s[98:99]
	v_pk_mul_f32 v[164:165], v[40:41], s[98:99]
	v_pk_mul_f32 v[166:167], v[42:43], s[98:99]
	v_exp_f32_e32 v148, v148
	v_exp_f32_e32 v149, v149
	v_exp_f32_e32 v150, v150
	v_exp_f32_e32 v151, v151
	v_exp_f32_e32 v164, v164
	v_exp_f32_e32 v165, v165
	v_exp_f32_e32 v166, v166
	v_exp_f32_e32 v167, v167
	v_pk_add_f32 v[148:149], v[148:149], 1.0 op_sel_hi:[1,0]
	v_pk_add_f32 v[150:151], v[150:151], 1.0 op_sel_hi:[1,0]
	v_pk_add_f32 v[164:165], v[164:165], 1.0 op_sel_hi:[1,0]
	v_pk_add_f32 v[166:167], v[166:167], 1.0 op_sel_hi:[1,0]
	v_rcp_f32_e32 v148, v148
	v_rcp_f32_e32 v149, v149
	v_rcp_f32_e32 v150, v150
	v_rcp_f32_e32 v151, v151
	v_rcp_f32_e32 v164, v164
	v_rcp_f32_e32 v165, v165
	v_rcp_f32_e32 v166, v166
	v_rcp_f32_e32 v167, v167
	v_pk_mul_f32 v[44:45], v[44:45], v[148:149]
	v_pk_mul_f32 v[46:47], v[46:47], v[150:151]
	v_pk_mul_f32 v[40:41], v[40:41], v[164:165]
	v_pk_mul_f32 v[42:43], v[42:43], v[166:167]
	v_cvt_pk_bf16_f32 v44, v44, v45
	v_cvt_pk_bf16_f32 v45, v46, v47
	v_cvt_pk_bf16_f32 v46, v40, v41
	v_cvt_pk_bf16_f32 v47, v42, v43
	global_store_dwordx4 v146, v[44:47], s[92:93] nt
	s_add_u32 s92, s86, 0xb0000
	s_addc_u32 s93, s87, 0
	v_pk_mul_f32 v[148:149], v[36:37], s[98:99]
	v_pk_mul_f32 v[150:151], v[38:39], s[98:99]
	v_pk_mul_f32 v[164:165], v[32:33], s[98:99]
	v_pk_mul_f32 v[166:167], v[34:35], s[98:99]
	v_exp_f32_e32 v148, v148
	v_exp_f32_e32 v149, v149
	v_exp_f32_e32 v150, v150
	v_exp_f32_e32 v151, v151
	v_exp_f32_e32 v164, v164
	v_exp_f32_e32 v165, v165
	v_exp_f32_e32 v166, v166
	v_exp_f32_e32 v167, v167
	v_pk_add_f32 v[148:149], v[148:149], 1.0 op_sel_hi:[1,0]
	v_pk_add_f32 v[150:151], v[150:151], 1.0 op_sel_hi:[1,0]
	v_pk_add_f32 v[164:165], v[164:165], 1.0 op_sel_hi:[1,0]
	v_pk_add_f32 v[166:167], v[166:167], 1.0 op_sel_hi:[1,0]
	v_rcp_f32_e32 v148, v148
	v_rcp_f32_e32 v149, v149
	v_rcp_f32_e32 v150, v150
	v_rcp_f32_e32 v151, v151
	v_rcp_f32_e32 v164, v164
	v_rcp_f32_e32 v165, v165
	v_rcp_f32_e32 v166, v166
	v_rcp_f32_e32 v167, v167
	v_pk_mul_f32 v[36:37], v[36:37], v[148:149]
	v_pk_mul_f32 v[38:39], v[38:39], v[150:151]
	v_pk_mul_f32 v[32:33], v[32:33], v[164:165]
	v_pk_mul_f32 v[34:35], v[34:35], v[166:167]
	v_cvt_pk_bf16_f32 v36, v36, v37
	v_cvt_pk_bf16_f32 v37, v38, v39
	v_cvt_pk_bf16_f32 v38, v32, v33
	v_cvt_pk_bf16_f32 v39, v34, v35
	global_store_dwordx4 v146, v[36:39], s[92:93] nt
	s_add_u32 s92, s86, 0x80100
	s_addc_u32 s93, s87, 0
	v_pk_mul_f32 v[148:149], v[28:29], s[98:99]
	v_pk_mul_f32 v[150:151], v[30:31], s[98:99]
	v_pk_mul_f32 v[164:165], v[24:25], s[98:99]
	v_pk_mul_f32 v[166:167], v[26:27], s[98:99]
	v_exp_f32_e32 v148, v148
	v_exp_f32_e32 v149, v149
	v_exp_f32_e32 v150, v150
	v_exp_f32_e32 v151, v151
	v_exp_f32_e32 v164, v164
	v_exp_f32_e32 v165, v165
	v_exp_f32_e32 v166, v166
	v_exp_f32_e32 v167, v167
	v_pk_add_f32 v[148:149], v[148:149], 1.0 op_sel_hi:[1,0]
	v_pk_add_f32 v[150:151], v[150:151], 1.0 op_sel_hi:[1,0]
	v_pk_add_f32 v[164:165], v[164:165], 1.0 op_sel_hi:[1,0]
	v_pk_add_f32 v[166:167], v[166:167], 1.0 op_sel_hi:[1,0]
	v_rcp_f32_e32 v148, v148
	v_rcp_f32_e32 v149, v149
	v_rcp_f32_e32 v150, v150
	v_rcp_f32_e32 v151, v151
	v_rcp_f32_e32 v164, v164
	v_rcp_f32_e32 v165, v165
	v_rcp_f32_e32 v166, v166
	v_rcp_f32_e32 v167, v167
	v_pk_mul_f32 v[28:29], v[28:29], v[148:149]
	v_pk_mul_f32 v[30:31], v[30:31], v[150:151]
	v_pk_mul_f32 v[24:25], v[24:25], v[164:165]
	v_pk_mul_f32 v[26:27], v[26:27], v[166:167]
	v_cvt_pk_bf16_f32 v28, v28, v29
	v_cvt_pk_bf16_f32 v29, v30, v31
	v_cvt_pk_bf16_f32 v30, v24, v25
	v_cvt_pk_bf16_f32 v31, v26, v27
	global_store_dwordx4 v146, v[28:31], s[92:93] nt
	s_add_u32 s92, s86, 0x90100
; __device__ __forceinline__ unsigned pk_bf16(float lo, float hi) { const f32x2 v = {lo, hi}; return __builtin_bit_cast(unsigned, __builtin_convertvector(v, nbf16x2)); }
; __device__ __forceinline__ void st8_bf16(bf16_t* p, const f32x4 a, const f32x4 b) { __builtin_nontemporal_store((u32x4){pk_bf16(a[0], a[1]), pk_bf16(a[2], a[3]), pk_bf16(b[0], b[1]), pk_bf16(b[2], b[3])}, (u32x4*)p); }
; __device__ __forceinline__ void st8_f32(float* p, const f32x4 a, const f32x4 b) { __builtin_nontemporal_store(a, (f32x4*)p); __builtin_nontemporal_store(b, (f32x4*)(p + 4)); }
; __device__ __forceinline__ f32x4 silu4(const f32x4 v) { return (f32x4){v[0] / (1.f + __expf(-v[0])), v[1] / (1.f + __expf(-v[1])), v[2] / (1.f + __expf(-v[2])), v[3] / (1.f + __expf(-v[3]))}; }
;     __device__ __forceinline__ void store8(int row, int col, const f32x4 v, const f32x4 w) const {
;         if (col < 1536) st8_bf16((bf16_t*)(ws + WS_BRANCH) + (size_t)row * BR + col, v, w);
;         else if (col < 3072) { const int c = col - 1536; st8_bf16((bf16_t*)(ws + WS_KB) + (size_t)row * MIXW + c, v, w);
;             if (row < MP) st8_f32(out + O_PK + (size_t)row * MIXW + c, v, w); else st8_f32(out + O_SK + (size_t)(row - MP) * MIXW + c, v, w); }
;         else if (col < 4608) { const int c = col - 3072; st8_bf16((bf16_t*)(ws + WS_VB) + (size_t)row * MIXW + c, v, w);
;             if (row < MP) st8_f32(out + O_PV + (size_t)row * MIXW + c, v, w); else st8_f32(out + O_SV + (size_t)(row - MP) * MIXW + c, v, w); }
;         else if (col < 5120) st8_bf16((bf16_t*)(ws + WS_BRANCH) + (size_t)row * BR + 1536 + (col - 4608), v, w);
;         else st8_bf16((bf16_t*)(ws + WS_GATE) + (size_t)row * BR + (col - 5120), silu4(v), silu4(w));
	s_addc_u32 s93, s87, 0
	v_pk_mul_f32 v[148:149], v[20:21], s[98:99]
	v_pk_mul_f32 v[150:151], v[22:23], s[98:99]
	v_pk_mul_f32 v[164:165], v[16:17], s[98:99]
	v_pk_mul_f32 v[166:167], v[18:19], s[98:99]
	v_exp_f32_e32 v148, v148
	v_exp_f32_e32 v149, v149
	v_exp_f32_e32 v150, v150
	v_exp_f32_e32 v151, v151
	v_exp_f32_e32 v164, v164
	v_exp_f32_e32 v165, v165
	v_exp_f32_e32 v166, v166
	v_exp_f32_e32 v167, v167
	v_pk_add_f32 v[148:149], v[148:149], 1.0 op_sel_hi:[1,0]
	v_pk_add_f32 v[150:151], v[150:151], 1.0 op_sel_hi:[1,0]
	v_pk_add_f32 v[164:165], v[164:165], 1.0 op_sel_hi:[1,0]
	v_pk_add_f32 v[166:167], v[166:167], 1.0 op_sel_hi:[1,0]
	v_rcp_f32_e32 v148, v148
	v_rcp_f32_e32 v149, v149
	v_rcp_f32_e32 v150, v150
	v_rcp_f32_e32 v151, v151
	v_rcp_f32_e32 v164, v164
	v_rcp_f32_e32 v165, v165
	v_rcp_f32_e32 v166, v166
	v_rcp_f32_e32 v167, v167
	v_pk_mul_f32 v[20:21], v[20:21], v[148:149]
	v_pk_mul_f32 v[22:23], v[22:23], v[150:151]
	v_pk_mul_f32 v[16:17], v[16:17], v[164:165]
	v_pk_mul_f32 v[18:19], v[18:19], v[166:167]
	v_cvt_pk_bf16_f32 v20, v20, v21
	v_cvt_pk_bf16_f32 v21, v22, v23
	v_cvt_pk_bf16_f32 v22, v16, v17
	v_cvt_pk_bf16_f32 v23, v18, v19
	global_store_dwordx4 v146, v[20:23], s[92:93] nt
	s_add_u32 s92, s86, 0xa0100
	s_addc_u32 s93, s87, 0
	v_pk_mul_f32 v[148:149], v[12:13], s[98:99]
	v_pk_mul_f32 v[150:151], v[14:15], s[98:99]
	v_pk_mul_f32 v[164:165], v[8:9], s[98:99]
	v_pk_mul_f32 v[166:167], v[10:11], s[98:99]
	v_exp_f32_e32 v148, v148
	v_exp_f32_e32 v149, v149
	v_exp_f32_e32 v150, v150
	v_exp_f32_e32 v151, v151
	v_exp_f32_e32 v164, v164
	v_exp_f32_e32 v165, v165
	v_exp_f32_e32 v166, v166
	v_exp_f32_e32 v167, v167
	v_pk_add_f32 v[148:149], v[148:149], 1.0 op_sel_hi:[1,0]
	v_pk_add_f32 v[150:151], v[150:151], 1.0 op_sel_hi:[1,0]
	v_pk_add_f32 v[164:165], v[164:165], 1.0 op_sel_hi:[1,0]
	v_pk_add_f32 v[166:167], v[166:167], 1.0 op_sel_hi:[1,0]
	v_rcp_f32_e32 v148, v148
	v_rcp_f32_e32 v149, v149
	v_rcp_f32_e32 v150, v150
	v_rcp_f32_e32 v151, v151
	v_rcp_f32_e32 v164, v164
	v_rcp_f32_e32 v165, v165
	v_rcp_f32_e32 v166, v166
	v_rcp_f32_e32 v167, v167
	v_pk_mul_f32 v[12:13], v[12:13], v[148:149]
	v_pk_mul_f32 v[14:15], v[14:15], v[150:151]
	v_pk_mul_f32 v[8:9], v[8:9], v[164:165]
	v_pk_mul_f32 v[10:11], v[10:11], v[166:167]
	v_cvt_pk_bf16_f32 v12, v12, v13
	v_cvt_pk_bf16_f32 v13, v14, v15
	v_cvt_pk_bf16_f32 v14, v8, v9
	v_cvt_pk_bf16_f32 v15, v10, v11
	global_store_dwordx4 v146, v[12:15], s[92:93] nt
	s_add_u32 s92, s86, 0xb0100
	s_addc_u32 s93, s87, 0
	v_pk_mul_f32 v[148:149], v[4:5], s[98:99]
	v_pk_mul_f32 v[150:151], v[6:7], s[98:99]
	v_pk_mul_f32 v[164:165], v[0:1], s[98:99]
	v_pk_mul_f32 v[166:167], v[2:3], s[98:99]
	v_exp_f32_e32 v148, v148
	v_exp_f32_e32 v149, v149
	v_exp_f32_e32 v150, v150
	v_exp_f32_e32 v151, v151
	v_exp_f32_e32 v164, v164
	v_exp_f32_e32 v165, v165
	v_exp_f32_e32 v166, v166
	v_exp_f32_e32 v167, v167
	v_pk_add_f32 v[148:149], v[148:149], 1.0 op_sel_hi:[1,0]
	v_pk_add_f32 v[150:151], v[150:151], 1.0 op_sel_hi:[1,0]
	v_pk_add_f32 v[164:165], v[164:165], 1.0 op_sel_hi:[1,0]
	v_pk_add_f32 v[166:167], v[166:167], 1.0 op_sel_hi:[1,0]
	v_rcp_f32_e32 v148, v148
	v_rcp_f32_e32 v149, v149
	v_rcp_f32_e32 v150, v150
	v_rcp_f32_e32 v151, v151
	v_rcp_f32_e32 v164, v164
	v_rcp_f32_e32 v165, v165
	v_rcp_f32_e32 v166, v166
	v_rcp_f32_e32 v167, v167
	v_pk_mul_f32 v[4:5], v[4:5], v[148:149]
	v_pk_mul_f32 v[6:7], v[6:7], v[150:151]
	v_pk_mul_f32 v[0:1], v[0:1], v[164:165]
	v_pk_mul_f32 v[2:3], v[2:3], v[166:167]
	v_cvt_pk_bf16_f32 v4, v4, v5
	v_cvt_pk_bf16_f32 v5, v6, v7
	v_cvt_pk_bf16_f32 v6, v0, v1
	v_cvt_pk_bf16_f32 v7, v2, v3
	global_store_dwordx4 v146, v[4:7], s[92:93] nt
	s_branch .Le6_done
.Le6_q:
	s_mul_i32 s85, s84, 0x1000
	s_add_u32 s86, s14, s85
	s_addc_u32 s87, s15, 0
	s_add_u32 s86, s86, 0x58e0000
	s_addc_u32 s87, s87, 0
	s_sub_i32 s85, s6, 0
	s_lshl_b32 s85, s85, 9
	s_add_u32 s86, s86, s85
	s_addc_u32 s87, s87, 0
	v_lshlrev_b32_e32 v146, 1, v154
	s_movk_i32 s85, 0x1000
	v_mad_u32_u24 v146, v152, s85, v146
	s_mov_b64 s[92:93], s[86:87]
	v_cvt_pk_bf16_f32 v158, v124, v125
	v_cvt_pk_bf16_f32 v159, v126, v127
	v_cvt_pk_bf16_f32 v160, v120, v121
	v_cvt_pk_bf16_f32 v161, v122, v123
	global_store_dwordx4 v146, v[158:161], s[92:93] nt
	s_add_u32 s92, s86, 0x10000
	s_addc_u32 s93, s87, 0
	v_cvt_pk_bf16_f32 v162, v116, v117
	v_cvt_pk_bf16_f32 v163, v118, v119
	v_cvt_pk_bf16_f32 v164, v112, v113
	v_cvt_pk_bf16_f32 v165, v114, v115
	global_store_dwordx4 v146, v[162:165], s[92:93] nt
	s_add_u32 s92, s86, 0x20000
	s_addc_u32 s93, s87, 0
	v_cvt_pk_bf16_f32 v158, v108, v109
	v_cvt_pk_bf16_f32 v159, v110, v111
	v_cvt_pk_bf16_f32 v160, v104, v105
	v_cvt_pk_bf16_f32 v161, v106, v107
	global_store_dwordx4 v146, v[158:161], s[92:93] nt
	s_add_u32 s92, s86, 0x30000
	s_addc_u32 s93, s87, 0
	v_cvt_pk_bf16_f32 v162, v100, v101
	v_cvt_pk_bf16_f32 v163, v102, v103
	v_cvt_pk_bf16_f32 v164, v96, v97
	v_cvt_pk_bf16_f32 v165, v98, v99
	global_store_dwordx4 v146, v[162:165], s[92:93] nt
	s_add_u32 s92, s86, 0x100
	s_addc_u32 s93, s87, 0
	v_cvt_pk_bf16_f32 v158, v92, v93
	v_cvt_pk_bf16_f32 v159, v94, v95
	v_cvt_pk_bf16_f32 v160, v88, v89
	v_cvt_pk_bf16_f32 v161, v90, v91
	global_store_dwordx4 v146, v[158:161], s[92:93] nt
	s_add_u32 s92, s86, 0x10100
	s_addc_u32 s93, s87, 0
	v_cvt_pk_bf16_f32 v162, v84, v85
	v_cvt_pk_bf16_f32 v163, v86, v87
	v_cvt_pk_bf16_f32 v164, v80, v81
	v_cvt_pk_bf16_f32 v165, v82, v83
	global_store_dwordx4 v146, v[162:165], s[92:93] nt
	s_add_u32 s92, s86, 0x20100
	s_addc_u32 s93, s87, 0
	v_cvt_pk_bf16_f32 v158, v76, v77
	v_cvt_pk_bf16_f32 v159, v78, v79
	v_cvt_pk_bf16_f32 v160, v72, v73
	v_cvt_pk_bf16_f32 v161, v74, v75
; __device__ __forceinline__ void st8_bf16(bf16_t* p, const f32x4 a, const f32x4 b) { __builtin_nontemporal_store((u32x4){pk_bf16(a[0], a[1]), pk_bf16(a[2], a[3]), pk_bf16(b[0], b[1]), pk_bf16(b[2], b[3])}, (u32x4*)p); }
; __device__ __forceinline__ void st8_f32(float* p, const f32x4 a, const f32x4 b) { __builtin_nontemporal_store(a, (f32x4*)p); __builtin_nontemporal_store(b, (f32x4*)(p + 4)); }
;     __device__ __forceinline__ void store8(int row, int col, const f32x4 v, const f32x4 w) const {
;         if (col < 1536) st8_bf16((bf16_t*)(ws + WS_BRANCH) + (size_t)row * BR + col, v, w);
;         else if (col < 3072) { const int c = col - 1536; st8_bf16((bf16_t*)(ws + WS_KB) + (size_t)row * MIXW + c, v, w);
;             if (row < MP) st8_f32(out + O_PK + (size_t)row * MIXW + c, v, w); else st8_f32(out + O_SK + (size_t)(row - MP) * MIXW + c, v, w); }
;         else if (col < 4608) { const int c = col - 3072; st8_bf16((bf16_t*)(ws + WS_VB) + (size_t)row * MIXW + c, v, w);
;             if (row < MP) st8_f32(out + O_PV + (size_t)row * MIXW + c, v, w); else st8_f32(out + O_SV + (size_t)(row - MP) * MIXW + c, v, w); }
;         else if (col < 5120) st8_bf16((bf16_t*)(ws + WS_BRANCH) + (size_t)row * BR + 1536 + (col - 4608), v, w);
	global_store_dwordx4 v146, v[158:161], s[92:93] nt
	s_add_u32 s92, s86, 0x30100
	s_addc_u32 s93, s87, 0
	v_cvt_pk_bf16_f32 v162, v68, v69
	v_cvt_pk_bf16_f32 v163, v70, v71
	v_cvt_pk_bf16_f32 v164, v64, v65
	v_cvt_pk_bf16_f32 v165, v66, v67
	global_store_dwordx4 v146, v[162:165], s[92:93] nt
	s_add_u32 s92, s86, 0x80000
	s_addc_u32 s93, s87, 0
	v_cvt_pk_bf16_f32 v158, v60, v61
	v_cvt_pk_bf16_f32 v159, v62, v63
	v_cvt_pk_bf16_f32 v160, v56, v57
	v_cvt_pk_bf16_f32 v161, v58, v59
	global_store_dwordx4 v146, v[158:161], s[92:93] nt
	s_add_u32 s92, s86, 0x90000
	s_addc_u32 s93, s87, 0
	v_cvt_pk_bf16_f32 v162, v52, v53
	v_cvt_pk_bf16_f32 v163, v54, v55
	v_cvt_pk_bf16_f32 v164, v48, v49
	v_cvt_pk_bf16_f32 v165, v50, v51
	global_store_dwordx4 v146, v[162:165], s[92:93] nt
	s_add_u32 s92, s86, 0xa0000
	s_addc_u32 s93, s87, 0
	v_cvt_pk_bf16_f32 v158, v44, v45
	v_cvt_pk_bf16_f32 v159, v46, v47
	v_cvt_pk_bf16_f32 v160, v40, v41
	v_cvt_pk_bf16_f32 v161, v42, v43
	global_store_dwordx4 v146, v[158:161], s[92:93] nt
	s_add_u32 s92, s86, 0xb0000
	s_addc_u32 s93, s87, 0
	v_cvt_pk_bf16_f32 v162, v36, v37
	v_cvt_pk_bf16_f32 v163, v38, v39
	v_cvt_pk_bf16_f32 v164, v32, v33
	v_cvt_pk_bf16_f32 v165, v34, v35
	global_store_dwordx4 v146, v[162:165], s[92:93] nt
	s_add_u32 s92, s86, 0x80100
	s_addc_u32 s93, s87, 0
	v_cvt_pk_bf16_f32 v158, v28, v29
	v_cvt_pk_bf16_f32 v159, v30, v31
	v_cvt_pk_bf16_f32 v160, v24, v25
	v_cvt_pk_bf16_f32 v161, v26, v27
	global_store_dwordx4 v146, v[158:161], s[92:93] nt
	s_add_u32 s92, s86, 0x90100
	s_addc_u32 s93, s87, 0
	v_cvt_pk_bf16_f32 v162, v20, v21
	v_cvt_pk_bf16_f32 v163, v22, v23
	v_cvt_pk_bf16_f32 v164, v16, v17
	v_cvt_pk_bf16_f32 v165, v18, v19
	global_store_dwordx4 v146, v[162:165], s[92:93] nt
	s_add_u32 s92, s86, 0xa0100
	s_addc_u32 s93, s87, 0
	v_cvt_pk_bf16_f32 v158, v12, v13
	v_cvt_pk_bf16_f32 v159, v14, v15
	v_cvt_pk_bf16_f32 v160, v8, v9
	v_cvt_pk_bf16_f32 v161, v10, v11
	global_store_dwordx4 v146, v[158:161], s[92:93] nt
	s_add_u32 s92, s86, 0xb0100
	s_addc_u32 s93, s87, 0
	v_cvt_pk_bf16_f32 v162, v4, v5
	v_cvt_pk_bf16_f32 v163, v6, v7
	v_cvt_pk_bf16_f32 v164, v0, v1
	v_cvt_pk_bf16_f32 v165, v2, v3
	global_store_dwordx4 v146, v[162:165], s[92:93] nt
	s_branch .Le6_done
.Le6_b2:
	s_mul_i32 s85, s84, 0x1000
	s_add_u32 s86, s14, s85
	s_addc_u32 s87, s15, 0
	s_add_u32 s86, s86, 0x58e0c00
	s_addc_u32 s87, s87, 0
	s_sub_i32 s85, s6, 18
	s_lshl_b32 s85, s85, 9
	s_add_u32 s86, s86, s85
	s_addc_u32 s87, s87, 0
	v_lshlrev_b32_e32 v146, 1, v154
	s_movk_i32 s85, 0x1000
	v_mad_u32_u24 v146, v152, s85, v146
	s_mov_b64 s[92:93], s[86:87]
	v_cvt_pk_bf16_f32 v158, v124, v125
	v_cvt_pk_bf16_f32 v159, v126, v127
	v_cvt_pk_bf16_f32 v160, v120, v121
	v_cvt_pk_bf16_f32 v161, v122, v123
	global_store_dwordx4 v146, v[158:161], s[92:93] nt
	s_add_u32 s92, s86, 0x10000
	s_addc_u32 s93, s87, 0
	v_cvt_pk_bf16_f32 v162, v116, v117
	v_cvt_pk_bf16_f32 v163, v118, v119
	v_cvt_pk_bf16_f32 v164, v112, v113
	v_cvt_pk_bf16_f32 v165, v114, v115
	global_store_dwordx4 v146, v[162:165], s[92:93] nt
	s_add_u32 s92, s86, 0x20000
	s_addc_u32 s93, s87, 0
	v_cvt_pk_bf16_f32 v158, v108, v109
	v_cvt_pk_bf16_f32 v159, v110, v111
	v_cvt_pk_bf16_f32 v160, v104, v105
	v_cvt_pk_bf16_f32 v161, v106, v107
	global_store_dwordx4 v146, v[158:161], s[92:93] nt
	s_add_u32 s92, s86, 0x30000
	s_addc_u32 s93, s87, 0
	v_cvt_pk_bf16_f32 v162, v100, v101
	v_cvt_pk_bf16_f32 v163, v102, v103
	v_cvt_pk_bf16_f32 v164, v96, v97
	v_cvt_pk_bf16_f32 v165, v98, v99
	global_store_dwordx4 v146, v[162:165], s[92:93] nt
	s_add_u32 s92, s86, 0x100
	s_addc_u32 s93, s87, 0
	v_cvt_pk_bf16_f32 v158, v92, v93
	v_cvt_pk_bf16_f32 v159, v94, v95
	v_cvt_pk_bf16_f32 v160, v88, v89
	v_cvt_pk_bf16_f32 v161, v90, v91
	global_store_dwordx4 v146, v[158:161], s[92:93] nt
	s_add_u32 s92, s86, 0x10100
	s_addc_u32 s93, s87, 0
	v_cvt_pk_bf16_f32 v162, v84, v85
	v_cvt_pk_bf16_f32 v163, v86, v87
	v_cvt_pk_bf16_f32 v164, v80, v81
	v_cvt_pk_bf16_f32 v165, v82, v83
	global_store_dwordx4 v146, v[162:165], s[92:93] nt
	s_add_u32 s92, s86, 0x20100
	s_addc_u32 s93, s87, 0
	v_cvt_pk_bf16_f32 v158, v76, v77
	v_cvt_pk_bf16_f32 v159, v78, v79
	v_cvt_pk_bf16_f32 v160, v72, v73
	v_cvt_pk_bf16_f32 v161, v74, v75
	global_store_dwordx4 v146, v[158:161], s[92:93] nt
	s_add_u32 s92, s86, 0x30100
	s_addc_u32 s93, s87, 0
	v_cvt_pk_bf16_f32 v162, v68, v69
	v_cvt_pk_bf16_f32 v163, v70, v71
	v_cvt_pk_bf16_f32 v164, v64, v65
	v_cvt_pk_bf16_f32 v165, v66, v67
	global_store_dwordx4 v146, v[162:165], s[92:93] nt
	s_add_u32 s92, s86, 0x80000
	s_addc_u32 s93, s87, 0
	v_cvt_pk_bf16_f32 v158, v60, v61
	v_cvt_pk_bf16_f32 v159, v62, v63
	v_cvt_pk_bf16_f32 v160, v56, v57
	v_cvt_pk_bf16_f32 v161, v58, v59
	global_store_dwordx4 v146, v[158:161], s[92:93] nt
	s_add_u32 s92, s86, 0x90000
	s_addc_u32 s93, s87, 0
	v_cvt_pk_bf16_f32 v162, v52, v53
	v_cvt_pk_bf16_f32 v163, v54, v55
	v_cvt_pk_bf16_f32 v164, v48, v49
	v_cvt_pk_bf16_f32 v165, v50, v51
	global_store_dwordx4 v146, v[162:165], s[92:93] nt
	s_add_u32 s92, s86, 0xa0000
	s_addc_u32 s93, s87, 0
	v_cvt_pk_bf16_f32 v158, v44, v45
	v_cvt_pk_bf16_f32 v159, v46, v47
	v_cvt_pk_bf16_f32 v160, v40, v41
	v_cvt_pk_bf16_f32 v161, v42, v43
	global_store_dwordx4 v146, v[158:161], s[92:93] nt
	s_add_u32 s92, s86, 0xb0000
	s_addc_u32 s93, s87, 0
	v_cvt_pk_bf16_f32 v162, v36, v37
	v_cvt_pk_bf16_f32 v163, v38, v39
	v_cvt_pk_bf16_f32 v164, v32, v33
	v_cvt_pk_bf16_f32 v165, v34, v35
	global_store_dwordx4 v146, v[162:165], s[92:93] nt
	s_add_u32 s92, s86, 0x80100
	s_addc_u32 s93, s87, 0
	v_cvt_pk_bf16_f32 v158, v28, v29
	v_cvt_pk_bf16_f32 v159, v30, v31
	v_cvt_pk_bf16_f32 v160, v24, v25
	v_cvt_pk_bf16_f32 v161, v26, v27
	global_store_dwordx4 v146, v[158:161], s[92:93] nt
	s_add_u32 s92, s86, 0x90100
	s_addc_u32 s93, s87, 0
	v_cvt_pk_bf16_f32 v162, v20, v21
	v_cvt_pk_bf16_f32 v163, v22, v23
	v_cvt_pk_bf16_f32 v164, v16, v17
	v_cvt_pk_bf16_f32 v165, v18, v19
	global_store_dwordx4 v146, v[162:165], s[92:93] nt
	s_add_u32 s92, s86, 0xa0100
	s_addc_u32 s93, s87, 0
	v_cvt_pk_bf16_f32 v158, v12, v13
	v_cvt_pk_bf16_f32 v159, v14, v15
	v_cvt_pk_bf16_f32 v160, v8, v9
	v_cvt_pk_bf16_f32 v161, v10, v11
	global_store_dwordx4 v146, v[158:161], s[92:93] nt
	s_add_u32 s92, s86, 0xb0100
	s_addc_u32 s93, s87, 0
	v_cvt_pk_bf16_f32 v162, v4, v5
	v_cvt_pk_bf16_f32 v163, v6, v7
	v_cvt_pk_bf16_f32 v164, v0, v1
	v_cvt_pk_bf16_f32 v165, v2, v3
	global_store_dwordx4 v146, v[162:165], s[92:93] nt
	s_branch .Le6_done
; __device__ __forceinline__ unsigned pk_bf16(float lo, float hi) { const f32x2 v = {lo, hi}; return __builtin_bit_cast(unsigned, __builtin_convertvector(v, nbf16x2)); }
; __device__ __forceinline__ void st8_bf16(bf16_t* p, const f32x4 a, const f32x4 b) { __builtin_nontemporal_store((u32x4){pk_bf16(a[0], a[1]), pk_bf16(a[2], a[3]), pk_bf16(b[0], b[1]), pk_bf16(b[2], b[3])}, (u32x4*)p); }
; __device__ __forceinline__ void st8_f32(float* p, const f32x4 a, const f32x4 b) { __builtin_nontemporal_store(a, (f32x4*)p); __builtin_nontemporal_store(b, (f32x4*)(p + 4)); }
;     __device__ __forceinline__ void store8(int row, int col, const f32x4 v, const f32x4 w) const {
;     ...
;         else if (col < 3072) { const int c = col - 1536; st8_bf16((bf16_t*)(ws + WS_KB) + (size_t)row * MIXW + c, v, w);
;             if (row < MP) st8_f32(out + O_PK + (size_t)row * MIXW + c, v, w); else st8_f32(out + O_SK + (size_t)(row - MP) * MIXW + c, v, w); }
.Le6_k:
	s_mul_i32 s85, s84, 0xc00
	s_add_u32 s86, s14, s85
	s_addc_u32 s87, s15, 0
	s_add_u32 s86, s86, 0x25ce0000
	s_addc_u32 s87, s87, 0
	s_sub_i32 s85, s6, 6
	s_lshl_b32 s85, s85, 9
	s_add_u32 s86, s86, s85
	s_addc_u32 s87, s87, 0
	v_lshlrev_b32_e32 v146, 1, v154
	s_movk_i32 s85, 0xc00
	v_mad_u32_u24 v146, v152, s85, v146
	s_cmp_lt_u32 s8, 0x100
	s_cbranch_scc1 .Le6_k_prompt
	s_sub_i32 s85, s84, 0x10000
	s_mul_i32 s85, s85, 0x1800
	s_add_u32 s88, s12, 0x42e94000
	s_addc_u32 s89, s13, 0
	s_branch .Le6_k_rows
.Le6_k_prompt:
	s_mul_i32 s85, s84, 0x1800
	s_add_u32 s88, s12, 0x1084a000
	s_addc_u32 s89, s13, 0
.Le6_k_rows:
	s_add_u32 s88, s88, s85
	s_addc_u32 s89, s89, 0
	s_sub_i32 s85, s6, 6
	s_lshl_b32 s85, s85, 10
	s_add_u32 s88, s88, s85
	s_addc_u32 s89, s89, 0
	v_lshlrev_b32_e32 v147, 2, v154
	s_movk_i32 s85, 0x1800
	v_mad_u32_u24 v147, v152, s85, v147
	s_mov_b64 s[92:93], s[86:87]
	s_mov_b64 s[94:95], s[88:89]
	global_store_dwordx4 v147, v[124:127], s[94:95] nt
	global_store_dwordx4 v147, v[120:123], s[94:95] offset:16 nt
	v_cvt_pk_bf16_f32 v158, v124, v125
	v_cvt_pk_bf16_f32 v159, v126, v127
	v_cvt_pk_bf16_f32 v160, v120, v121
	v_cvt_pk_bf16_f32 v161, v122, v123
	global_store_dwordx4 v146, v[158:161], s[92:93] nt
	s_add_u32 s92, s86, 0xc000
	s_addc_u32 s93, s87, 0
	s_add_u32 s94, s88, 0x18000
	s_addc_u32 s95, s89, 0
	global_store_dwordx4 v147, v[116:119], s[94:95] nt
	global_store_dwordx4 v147, v[112:115], s[94:95] offset:16 nt
	v_cvt_pk_bf16_f32 v162, v116, v117
	v_cvt_pk_bf16_f32 v163, v118, v119
	v_cvt_pk_bf16_f32 v164, v112, v113
	v_cvt_pk_bf16_f32 v165, v114, v115
	global_store_dwordx4 v146, v[162:165], s[92:93] nt
	s_add_u32 s92, s86, 0x18000
	s_addc_u32 s93, s87, 0
	s_add_u32 s94, s88, 0x30000
	s_addc_u32 s95, s89, 0
	global_store_dwordx4 v147, v[108:111], s[94:95] nt
	global_store_dwordx4 v147, v[104:107], s[94:95] offset:16 nt
	v_cvt_pk_bf16_f32 v158, v108, v109
	v_cvt_pk_bf16_f32 v159, v110, v111
	v_cvt_pk_bf16_f32 v160, v104, v105
	v_cvt_pk_bf16_f32 v161, v106, v107
	global_store_dwordx4 v146, v[158:161], s[92:93] nt
	s_add_u32 s92, s86, 0x24000
	s_addc_u32 s93, s87, 0
	s_add_u32 s94, s88, 0x48000
	s_addc_u32 s95, s89, 0
	global_store_dwordx4 v147, v[100:103], s[94:95] nt
	global_store_dwordx4 v147, v[96:99], s[94:95] offset:16 nt
	v_cvt_pk_bf16_f32 v162, v100, v101
	v_cvt_pk_bf16_f32 v163, v102, v103
	v_cvt_pk_bf16_f32 v164, v96, v97
	v_cvt_pk_bf16_f32 v165, v98, v99
	global_store_dwordx4 v146, v[162:165], s[92:93] nt
	s_add_u32 s92, s86, 0x100
	s_addc_u32 s93, s87, 0
	s_add_u32 s94, s88, 0x200
	s_addc_u32 s95, s89, 0
	global_store_dwordx4 v147, v[92:95], s[94:95] nt
	global_store_dwordx4 v147, v[88:91], s[94:95] offset:16 nt
	v_cvt_pk_bf16_f32 v158, v92, v93
	v_cvt_pk_bf16_f32 v159, v94, v95
	v_cvt_pk_bf16_f32 v160, v88, v89
	v_cvt_pk_bf16_f32 v161, v90, v91
	global_store_dwordx4 v146, v[158:161], s[92:93] nt
	s_add_u32 s92, s86, 0xc100
	s_addc_u32 s93, s87, 0
	s_add_u32 s94, s88, 0x18200
	s_addc_u32 s95, s89, 0
	global_store_dwordx4 v147, v[84:87], s[94:95] nt
	global_store_dwordx4 v147, v[80:83], s[94:95] offset:16 nt
	v_cvt_pk_bf16_f32 v162, v84, v85
	v_cvt_pk_bf16_f32 v163, v86, v87
	v_cvt_pk_bf16_f32 v164, v80, v81
	v_cvt_pk_bf16_f32 v165, v82, v83
	global_store_dwordx4 v146, v[162:165], s[92:93] nt
	s_add_u32 s92, s86, 0x18100
	s_addc_u32 s93, s87, 0
	s_add_u32 s94, s88, 0x30200
	s_addc_u32 s95, s89, 0
	global_store_dwordx4 v147, v[76:79], s[94:95] nt
	global_store_dwordx4 v147, v[72:75], s[94:95] offset:16 nt
	v_cvt_pk_bf16_f32 v158, v76, v77
	v_cvt_pk_bf16_f32 v159, v78, v79
	v_cvt_pk_bf16_f32 v160, v72, v73
	v_cvt_pk_bf16_f32 v161, v74, v75
	global_store_dwordx4 v146, v[158:161], s[92:93] nt
	s_add_u32 s92, s86, 0x24100
	s_addc_u32 s93, s87, 0
	s_add_u32 s94, s88, 0x48200
	s_addc_u32 s95, s89, 0
	global_store_dwordx4 v147, v[68:71], s[94:95] nt
	global_store_dwordx4 v147, v[64:67], s[94:95] offset:16 nt
	v_cvt_pk_bf16_f32 v162, v68, v69
	v_cvt_pk_bf16_f32 v163, v70, v71
	v_cvt_pk_bf16_f32 v164, v64, v65
	v_cvt_pk_bf16_f32 v165, v66, v67
	global_store_dwordx4 v146, v[162:165], s[92:93] nt
	s_add_u32 s92, s86, 0x60000
	s_addc_u32 s93, s87, 0
	s_add_u32 s94, s88, 0xc0000
	s_addc_u32 s95, s89, 0
	global_store_dwordx4 v147, v[60:63], s[94:95] nt
	global_store_dwordx4 v147, v[56:59], s[94:95] offset:16 nt
	v_cvt_pk_bf16_f32 v158, v60, v61
	v_cvt_pk_bf16_f32 v159, v62, v63
	v_cvt_pk_bf16_f32 v160, v56, v57
	v_cvt_pk_bf16_f32 v161, v58, v59
	global_store_dwordx4 v146, v[158:161], s[92:93] nt
	s_add_u32 s92, s86, 0x6c000
	s_addc_u32 s93, s87, 0
	s_add_u32 s94, s88, 0xd8000
	s_addc_u32 s95, s89, 0
	global_store_dwordx4 v147, v[52:55], s[94:95] nt
	global_store_dwordx4 v147, v[48:51], s[94:95] offset:16 nt
	v_cvt_pk_bf16_f32 v162, v52, v53
	v_cvt_pk_bf16_f32 v163, v54, v55
	v_cvt_pk_bf16_f32 v164, v48, v49
	v_cvt_pk_bf16_f32 v165, v50, v51
	global_store_dwordx4 v146, v[162:165], s[92:93] nt
	s_add_u32 s92, s86, 0x78000
	s_addc_u32 s93, s87, 0
	s_add_u32 s94, s88, 0xf0000
	s_addc_u32 s95, s89, 0
	global_store_dwordx4 v147, v[44:47], s[94:95] nt
	global_store_dwordx4 v147, v[40:43], s[94:95] offset:16 nt
	v_cvt_pk_bf16_f32 v158, v44, v45
	v_cvt_pk_bf16_f32 v159, v46, v47
	v_cvt_pk_bf16_f32 v160, v40, v41
	v_cvt_pk_bf16_f32 v161, v42, v43
	global_store_dwordx4 v146, v[158:161], s[92:93] nt
	s_add_u32 s92, s86, 0x84000
	s_addc_u32 s93, s87, 0
	s_add_u32 s94, s88, 0x108000
	s_addc_u32 s95, s89, 0
	global_store_dwordx4 v147, v[36:39], s[94:95] nt
	global_store_dwordx4 v147, v[32:35], s[94:95] offset:16 nt
	v_cvt_pk_bf16_f32 v162, v36, v37
	v_cvt_pk_bf16_f32 v163, v38, v39
	v_cvt_pk_bf16_f32 v164, v32, v33
	v_cvt_pk_bf16_f32 v165, v34, v35
; __device__ __forceinline__ void st8_bf16(bf16_t* p, const f32x4 a, const f32x4 b) { __builtin_nontemporal_store((u32x4){pk_bf16(a[0], a[1]), pk_bf16(a[2], a[3]), pk_bf16(b[0], b[1]), pk_bf16(b[2], b[3])}, (u32x4*)p); }
; __device__ __forceinline__ void st8_f32(float* p, const f32x4 a, const f32x4 b) { __builtin_nontemporal_store(a, (f32x4*)p); __builtin_nontemporal_store(b, (f32x4*)(p + 4)); }
;     __device__ __forceinline__ void store8(int row, int col, const f32x4 v, const f32x4 w) const {
;     ...
;         else if (col < 3072) { const int c = col - 1536; st8_bf16((bf16_t*)(ws + WS_KB) + (size_t)row * MIXW + c, v, w);
;             if (row < MP) st8_f32(out + O_PK + (size_t)row * MIXW + c, v, w); else st8_f32(out + O_SK + (size_t)(row - MP) * MIXW + c, v, w); }
;         else if (col < 4608) { const int c = col - 3072; st8_bf16((bf16_t*)(ws + WS_VB) + (size_t)row * MIXW + c, v, w);
;             if (row < MP) st8_f32(out + O_PV + (size_t)row * MIXW + c, v, w); else st8_f32(out + O_SV + (size_t)(row - MP) * MIXW + c, v, w); }
	global_store_dwordx4 v146, v[162:165], s[92:93] nt
	s_add_u32 s92, s86, 0x60100
	s_addc_u32 s93, s87, 0
	s_add_u32 s94, s88, 0xc0200
	s_addc_u32 s95, s89, 0
	global_store_dwordx4 v147, v[28:31], s[94:95] nt
	global_store_dwordx4 v147, v[24:27], s[94:95] offset:16 nt
	v_cvt_pk_bf16_f32 v158, v28, v29
	v_cvt_pk_bf16_f32 v159, v30, v31
	v_cvt_pk_bf16_f32 v160, v24, v25
	v_cvt_pk_bf16_f32 v161, v26, v27
	global_store_dwordx4 v146, v[158:161], s[92:93] nt
	s_add_u32 s92, s86, 0x6c100
	s_addc_u32 s93, s87, 0
	s_add_u32 s94, s88, 0xd8200
	s_addc_u32 s95, s89, 0
	global_store_dwordx4 v147, v[20:23], s[94:95] nt
	global_store_dwordx4 v147, v[16:19], s[94:95] offset:16 nt
	v_cvt_pk_bf16_f32 v162, v20, v21
	v_cvt_pk_bf16_f32 v163, v22, v23
	v_cvt_pk_bf16_f32 v164, v16, v17
	v_cvt_pk_bf16_f32 v165, v18, v19
	global_store_dwordx4 v146, v[162:165], s[92:93] nt
	s_add_u32 s92, s86, 0x78100
	s_addc_u32 s93, s87, 0
	s_add_u32 s94, s88, 0xf0200
	s_addc_u32 s95, s89, 0
	global_store_dwordx4 v147, v[12:15], s[94:95] nt
	global_store_dwordx4 v147, v[8:11], s[94:95] offset:16 nt
	v_cvt_pk_bf16_f32 v158, v12, v13
	v_cvt_pk_bf16_f32 v159, v14, v15
	v_cvt_pk_bf16_f32 v160, v8, v9
	v_cvt_pk_bf16_f32 v161, v10, v11
	global_store_dwordx4 v146, v[158:161], s[92:93] nt
	s_add_u32 s92, s86, 0x84100
	s_addc_u32 s93, s87, 0
	s_add_u32 s94, s88, 0x108200
	s_addc_u32 s95, s89, 0
	global_store_dwordx4 v147, v[4:7], s[94:95] nt
	global_store_dwordx4 v147, v[0:3], s[94:95] offset:16 nt
	v_cvt_pk_bf16_f32 v162, v4, v5
	v_cvt_pk_bf16_f32 v163, v6, v7
	v_cvt_pk_bf16_f32 v164, v0, v1
	v_cvt_pk_bf16_f32 v165, v2, v3
	global_store_dwordx4 v146, v[162:165], s[92:93] nt
	s_branch .Le6_done
.Le6_v:
	s_mul_i32 s85, s84, 0xc00
	s_add_u32 s86, s14, s85
	s_addc_u32 s87, s15, 0
	s_add_u32 s86, s86, 0x31e60000
	s_addc_u32 s87, s87, 0
	s_sub_i32 s85, s6, 12
	s_lshl_b32 s85, s85, 9
	s_add_u32 s86, s86, s85
	s_addc_u32 s87, s87, 0
	v_lshlrev_b32_e32 v146, 1, v154
	s_movk_i32 s85, 0xc00
	v_mad_u32_u24 v146, v152, s85, v146
	s_cmp_lt_u32 s8, 0x100
	s_cbranch_scc1 .Le6_v_prompt
	s_sub_i32 s85, s84, 0x10000
	s_mul_i32 s85, s85, 0x1800
	s_add_u32 s88, s12, 0x43194000
	s_addc_u32 s89, s13, 0
	s_branch .Le6_v_rows
.Le6_v_prompt:
	s_mul_i32 s85, s84, 0x1800
	s_add_u32 s88, s12, 0x2884a000
	s_addc_u32 s89, s13, 0
; __device__ __forceinline__ unsigned pk_bf16(float lo, float hi) { const f32x2 v = {lo, hi}; return __builtin_bit_cast(unsigned, __builtin_convertvector(v, nbf16x2)); }
; __device__ __forceinline__ void st8_bf16(bf16_t* p, const f32x4 a, const f32x4 b) { __builtin_nontemporal_store((u32x4){pk_bf16(a[0], a[1]), pk_bf16(a[2], a[3]), pk_bf16(b[0], b[1]), pk_bf16(b[2], b[3])}, (u32x4*)p); }
; __device__ __forceinline__ void st8_f32(float* p, const f32x4 a, const f32x4 b) { __builtin_nontemporal_store(a, (f32x4*)p); __builtin_nontemporal_store(b, (f32x4*)(p + 4)); }
;     __device__ __forceinline__ void store8(int row, int col, const f32x4 v, const f32x4 w) const {
;     ...
;         else if (col < 4608) { const int c = col - 3072; st8_bf16((bf16_t*)(ws + WS_VB) + (size_t)row * MIXW + c, v, w);
;             if (row < MP) st8_f32(out + O_PV + (size_t)row * MIXW + c, v, w); else st8_f32(out + O_SV + (size_t)(row - MP) * MIXW + c, v, w); }
.Le6_v_rows:
	s_add_u32 s88, s88, s85
	s_addc_u32 s89, s89, 0
	s_sub_i32 s85, s6, 12
	s_lshl_b32 s85, s85, 10
	s_add_u32 s88, s88, s85
	s_addc_u32 s89, s89, 0
	v_lshlrev_b32_e32 v147, 2, v154
	s_movk_i32 s85, 0x1800
	v_mad_u32_u24 v147, v152, s85, v147
	s_mov_b64 s[92:93], s[86:87]
	s_mov_b64 s[94:95], s[88:89]
	global_store_dwordx4 v147, v[124:127], s[94:95] nt
	global_store_dwordx4 v147, v[120:123], s[94:95] offset:16 nt
	v_cvt_pk_bf16_f32 v158, v124, v125
	v_cvt_pk_bf16_f32 v159, v126, v127
	v_cvt_pk_bf16_f32 v160, v120, v121
	v_cvt_pk_bf16_f32 v161, v122, v123
	global_store_dwordx4 v146, v[158:161], s[92:93] nt
	s_add_u32 s92, s86, 0xc000
	s_addc_u32 s93, s87, 0
	s_add_u32 s94, s88, 0x18000
	s_addc_u32 s95, s89, 0
	global_store_dwordx4 v147, v[116:119], s[94:95] nt
	global_store_dwordx4 v147, v[112:115], s[94:95] offset:16 nt
	v_cvt_pk_bf16_f32 v162, v116, v117
	v_cvt_pk_bf16_f32 v163, v118, v119
	v_cvt_pk_bf16_f32 v164, v112, v113
	v_cvt_pk_bf16_f32 v165, v114, v115
	global_store_dwordx4 v146, v[162:165], s[92:93] nt
	s_add_u32 s92, s86, 0x18000
	s_addc_u32 s93, s87, 0
	s_add_u32 s94, s88, 0x30000
	s_addc_u32 s95, s89, 0
	global_store_dwordx4 v147, v[108:111], s[94:95] nt
	global_store_dwordx4 v147, v[104:107], s[94:95] offset:16 nt
	v_cvt_pk_bf16_f32 v158, v108, v109
	v_cvt_pk_bf16_f32 v159, v110, v111
	v_cvt_pk_bf16_f32 v160, v104, v105
	v_cvt_pk_bf16_f32 v161, v106, v107
	global_store_dwordx4 v146, v[158:161], s[92:93] nt
	s_add_u32 s92, s86, 0x24000
	s_addc_u32 s93, s87, 0
	s_add_u32 s94, s88, 0x48000
	s_addc_u32 s95, s89, 0
	global_store_dwordx4 v147, v[100:103], s[94:95] nt
	global_store_dwordx4 v147, v[96:99], s[94:95] offset:16 nt
	v_cvt_pk_bf16_f32 v162, v100, v101
	v_cvt_pk_bf16_f32 v163, v102, v103
	v_cvt_pk_bf16_f32 v164, v96, v97
	v_cvt_pk_bf16_f32 v165, v98, v99
	global_store_dwordx4 v146, v[162:165], s[92:93] nt
	s_add_u32 s92, s86, 0x100
	s_addc_u32 s93, s87, 0
	s_add_u32 s94, s88, 0x200
	s_addc_u32 s95, s89, 0
	global_store_dwordx4 v147, v[92:95], s[94:95] nt
	global_store_dwordx4 v147, v[88:91], s[94:95] offset:16 nt
	v_cvt_pk_bf16_f32 v158, v92, v93
	v_cvt_pk_bf16_f32 v159, v94, v95
	v_cvt_pk_bf16_f32 v160, v88, v89
	v_cvt_pk_bf16_f32 v161, v90, v91
	global_store_dwordx4 v146, v[158:161], s[92:93] nt
	s_add_u32 s92, s86, 0xc100
	s_addc_u32 s93, s87, 0
	s_add_u32 s94, s88, 0x18200
	s_addc_u32 s95, s89, 0
	global_store_dwordx4 v147, v[84:87], s[94:95] nt
	global_store_dwordx4 v147, v[80:83], s[94:95] offset:16 nt
	v_cvt_pk_bf16_f32 v162, v84, v85
	v_cvt_pk_bf16_f32 v163, v86, v87
	v_cvt_pk_bf16_f32 v164, v80, v81
	v_cvt_pk_bf16_f32 v165, v82, v83
	global_store_dwordx4 v146, v[162:165], s[92:93] nt
	s_add_u32 s92, s86, 0x18100
	s_addc_u32 s93, s87, 0
	s_add_u32 s94, s88, 0x30200
	s_addc_u32 s95, s89, 0
	global_store_dwordx4 v147, v[76:79], s[94:95] nt
	global_store_dwordx4 v147, v[72:75], s[94:95] offset:16 nt
	v_cvt_pk_bf16_f32 v158, v76, v77
	v_cvt_pk_bf16_f32 v159, v78, v79
	v_cvt_pk_bf16_f32 v160, v72, v73
	v_cvt_pk_bf16_f32 v161, v74, v75
	global_store_dwordx4 v146, v[158:161], s[92:93] nt
	s_add_u32 s92, s86, 0x24100
	s_addc_u32 s93, s87, 0
	s_add_u32 s94, s88, 0x48200
	s_addc_u32 s95, s89, 0
	global_store_dwordx4 v147, v[68:71], s[94:95] nt
	global_store_dwordx4 v147, v[64:67], s[94:95] offset:16 nt
	v_cvt_pk_bf16_f32 v162, v68, v69
	v_cvt_pk_bf16_f32 v163, v70, v71
	v_cvt_pk_bf16_f32 v164, v64, v65
	v_cvt_pk_bf16_f32 v165, v66, v67
	global_store_dwordx4 v146, v[162:165], s[92:93] nt
	s_add_u32 s92, s86, 0x60000
	s_addc_u32 s93, s87, 0
	s_add_u32 s94, s88, 0xc0000
	s_addc_u32 s95, s89, 0
	global_store_dwordx4 v147, v[60:63], s[94:95] nt
	global_store_dwordx4 v147, v[56:59], s[94:95] offset:16 nt
	v_cvt_pk_bf16_f32 v158, v60, v61
	v_cvt_pk_bf16_f32 v159, v62, v63
	v_cvt_pk_bf16_f32 v160, v56, v57
	v_cvt_pk_bf16_f32 v161, v58, v59
	global_store_dwordx4 v146, v[158:161], s[92:93] nt
	s_add_u32 s92, s86, 0x6c000
	s_addc_u32 s93, s87, 0
	s_add_u32 s94, s88, 0xd8000
	s_addc_u32 s95, s89, 0
	global_store_dwordx4 v147, v[52:55], s[94:95] nt
	global_store_dwordx4 v147, v[48:51], s[94:95] offset:16 nt
	v_cvt_pk_bf16_f32 v162, v52, v53
	v_cvt_pk_bf16_f32 v163, v54, v55
	v_cvt_pk_bf16_f32 v164, v48, v49
	v_cvt_pk_bf16_f32 v165, v50, v51
	global_store_dwordx4 v146, v[162:165], s[92:93] nt
	s_add_u32 s92, s86, 0x78000
	s_addc_u32 s93, s87, 0
	s_add_u32 s94, s88, 0xf0000
	s_addc_u32 s95, s89, 0
	global_store_dwordx4 v147, v[44:47], s[94:95] nt
	global_store_dwordx4 v147, v[40:43], s[94:95] offset:16 nt
	v_cvt_pk_bf16_f32 v158, v44, v45
	v_cvt_pk_bf16_f32 v159, v46, v47
	v_cvt_pk_bf16_f32 v160, v40, v41
	v_cvt_pk_bf16_f32 v161, v42, v43
	global_store_dwordx4 v146, v[158:161], s[92:93] nt
	s_add_u32 s92, s86, 0x84000
	s_addc_u32 s93, s87, 0
	s_add_u32 s94, s88, 0x108000
	s_addc_u32 s95, s89, 0
	global_store_dwordx4 v147, v[36:39], s[94:95] nt
	global_store_dwordx4 v147, v[32:35], s[94:95] offset:16 nt
	v_cvt_pk_bf16_f32 v162, v36, v37
	v_cvt_pk_bf16_f32 v163, v38, v39
	v_cvt_pk_bf16_f32 v164, v32, v33
	v_cvt_pk_bf16_f32 v165, v34, v35
	global_store_dwordx4 v146, v[162:165], s[92:93] nt
	s_add_u32 s92, s86, 0x60100
	s_addc_u32 s93, s87, 0
	s_add_u32 s94, s88, 0xc0200
	s_addc_u32 s95, s89, 0
	global_store_dwordx4 v147, v[28:31], s[94:95] nt
	global_store_dwordx4 v147, v[24:27], s[94:95] offset:16 nt
	v_cvt_pk_bf16_f32 v158, v28, v29
	v_cvt_pk_bf16_f32 v159, v30, v31
	v_cvt_pk_bf16_f32 v160, v24, v25
	v_cvt_pk_bf16_f32 v161, v26, v27
	global_store_dwordx4 v146, v[158:161], s[92:93] nt
	s_add_u32 s92, s86, 0x6c100
	s_addc_u32 s93, s87, 0
	s_add_u32 s94, s88, 0xd8200
	s_addc_u32 s95, s89, 0
	global_store_dwordx4 v147, v[20:23], s[94:95] nt
	global_store_dwordx4 v147, v[16:19], s[94:95] offset:16 nt
	v_cvt_pk_bf16_f32 v162, v20, v21
	v_cvt_pk_bf16_f32 v163, v22, v23
	v_cvt_pk_bf16_f32 v164, v16, v17
	v_cvt_pk_bf16_f32 v165, v18, v19
	global_store_dwordx4 v146, v[162:165], s[92:93] nt
	s_add_u32 s92, s86, 0x78100
	s_addc_u32 s93, s87, 0
	s_add_u32 s94, s88, 0xf0200
	s_addc_u32 s95, s89, 0
	global_store_dwordx4 v147, v[12:15], s[94:95] nt
	global_store_dwordx4 v147, v[8:11], s[94:95] offset:16 nt
	v_cvt_pk_bf16_f32 v158, v12, v13
	v_cvt_pk_bf16_f32 v159, v14, v15
	v_cvt_pk_bf16_f32 v160, v8, v9
	v_cvt_pk_bf16_f32 v161, v10, v11
	global_store_dwordx4 v146, v[158:161], s[92:93] nt
	s_add_u32 s92, s86, 0x84100
	s_addc_u32 s93, s87, 0
	s_add_u32 s94, s88, 0x108200
	s_addc_u32 s95, s89, 0
	global_store_dwordx4 v147, v[4:7], s[94:95] nt
	global_store_dwordx4 v147, v[0:3], s[94:95] offset:16 nt
	v_cvt_pk_bf16_f32 v162, v4, v5
	v_cvt_pk_bf16_f32 v163, v6, v7
	v_cvt_pk_bf16_f32 v164, v0, v1
	v_cvt_pk_bf16_f32 v165, v2, v3
	global_store_dwordx4 v146, v[162:165], s[92:93] nt
	s_branch .Le6_done
.Le6_done:
	s_andn2_b64 vcc, exec, s[4:5]
	s_mov_b64 s[4:5], -1
	s_cbranch_vccnz .LBB0_726
	s_andn2_b64 vcc, exec, s[16:17]
	s_cbranch_vccnz .LBB0_725
	s_barrier
	s_branch .LBB0_725
